# as v076 with the tiny GEMMs' MFMA-to-LDS-store distance padded to the table value (s_nop 6)
# speedup vs baseline: 1.0295x; 1.0013x over previous
.LBB0_286:
	v_ashrrev_i32_e32 v33, 31, v32
	v_lshlrev_b64 v[6:7], 11, v[32:33]
	v_lshl_add_u64 v[40:41], v[14:15], 0, v[6:7]
	v_add_co_u32_e32 v66, vcc, 0x8000, v40
	s_nop 0
	v_addc_co_u32_e32 v67, vcc, 0, v41, vcc
	global_load_dwordx4 v[100:103], v[12:13], off
	global_load_dwordx4 v[104:107], v[40:41], off
	global_load_dwordx4 v[108:111], v[66:67], off
	global_load_dwordx4 v[112:115], v[12:13], off offset:64
	global_load_dwordx4 v[116:119], v[40:41], off offset:64
	global_load_dwordx4 v[120:123], v[66:67], off offset:64
	global_load_dwordx4 v[124:127], v[12:13], off offset:128
	global_load_dwordx4 v[128:131], v[40:41], off offset:128
	global_load_dwordx4 v[132:135], v[66:67], off offset:128
	global_load_dwordx4 v[136:139], v[12:13], off offset:192
	global_load_dwordx4 v[140:143], v[40:41], off offset:192
	global_load_dwordx4 v[144:147], v[66:67], off offset:192
	s_waitcnt vmcnt(0)
	v_mfma_f32_16x16x32_bf16 v[6:9], v[100:103], v[104:107], 0
	v_mfma_f32_16x16x32_bf16 v[2:5], v[100:103], v[108:111], 0
	v_mfma_f32_16x16x32_bf16 v[6:9], v[112:115], v[116:119], v[6:9]
	v_mfma_f32_16x16x32_bf16 v[2:5], v[112:115], v[120:123], v[2:5]
	v_mfma_f32_16x16x32_bf16 v[6:9], v[124:127], v[128:131], v[6:9]
	v_mfma_f32_16x16x32_bf16 v[2:5], v[124:127], v[132:135], v[2:5]
	v_mfma_f32_16x16x32_bf16 v[6:9], v[136:139], v[140:143], v[6:9]
	v_mfma_f32_16x16x32_bf16 v[2:5], v[136:139], v[144:147], v[2:5]
	s_nop 6
	ds_write_b128 v1, v[6:9]
	s_nop 0
	ds_write_b128 v1, v[2:5] offset:1024
	s_waitcnt lgkmcnt(0)
	s_barrier
	s_and_saveexec_b64 s[8:9], s[2:3]
	s_cbranch_execz .LBB0_288
	ds_read_b128 v[36:39], v42 offset:2048
	ds_read_b128 v[46:49], v42 offset:3072
	ds_read_b128 v[50:53], v42 offset:4096
	s_waitcnt lgkmcnt(2)
	v_pk_add_f32 v[40:41], v[6:7], v[36:37]
	s_waitcnt lgkmcnt(1)
	v_pk_add_f32 v[48:49], v[4:5], v[48:49]
	ds_read_b128 v[4:7], v42 offset:5120
	v_pk_add_f32 v[8:9], v[8:9], v[38:39]
	v_pk_add_f32 v[2:3], v[2:3], v[46:47]
	ds_read_b128 v[36:39], v42 offset:6144
	s_waitcnt lgkmcnt(2)
	v_pk_add_f32 v[46:47], v[8:9], v[52:53]
	v_pk_add_f32 v[40:41], v[40:41], v[50:51]
	s_waitcnt lgkmcnt(1)
	v_pk_add_f32 v[48:49], v[48:49], v[6:7]
	ds_read_b128 v[6:9], v42 offset:7168
	v_pk_add_f32 v[50:51], v[2:3], v[4:5]
	ds_read_b128 v[2:5], v42 offset:8192
	s_waitcnt lgkmcnt(2)
	v_pk_add_f32 v[46:47], v[46:47], v[38:39]
	v_pk_add_f32 v[40:41], v[40:41], v[36:37]
	s_waitcnt lgkmcnt(1)
	v_pk_add_f32 v[8:9], v[48:49], v[8:9]
	ds_read_b128 v[36:39], v42 offset:9216
	v_pk_add_f32 v[48:49], v[50:51], v[6:7]
	s_waitcnt lgkmcnt(1)
	v_pk_add_f32 v[46:47], v[46:47], v[4:5]
	ds_read_b128 v[4:7], v42 offset:10240
	v_pk_add_f32 v[2:3], v[40:41], v[2:3]
	s_waitcnt lgkmcnt(1)
	v_pk_add_f32 v[50:51], v[8:9], v[38:39]
	ds_read_b128 v[38:41], v42 offset:11264
	v_pk_add_f32 v[36:37], v[48:49], v[36:37]
	s_waitcnt lgkmcnt(1)
	v_pk_add_f32 v[46:47], v[46:47], v[6:7]
	ds_read_b128 v[6:9], v42 offset:12288
	v_pk_add_f32 v[48:49], v[2:3], v[4:5]
	ds_read_b128 v[2:5], v42 offset:13312
	s_waitcnt lgkmcnt(2)
	v_pk_add_f32 v[40:41], v[50:51], v[40:41]
	v_pk_add_f32 v[50:51], v[36:37], v[38:39]
	s_waitcnt lgkmcnt(1)
	v_pk_add_f32 v[8:9], v[46:47], v[8:9]
	ds_read_b128 v[36:39], v42 offset:14336
	v_pk_add_f32 v[6:7], v[48:49], v[6:7]
	ds_read_b128 v[46:49], v42 offset:15360
	s_waitcnt lgkmcnt(2)
	v_pk_add_f32 v[4:5], v[40:41], v[4:5]
	v_pk_add_f32 v[2:3], v[50:51], v[2:3]
	s_waitcnt lgkmcnt(1)
	v_pk_add_f32 v[8:9], v[8:9], v[38:39]
	v_pk_add_f32 v[6:7], v[6:7], v[36:37]
	s_waitcnt lgkmcnt(0)
	v_pk_add_f32 v[4:5], v[4:5], v[48:49]
	v_pk_add_f32 v[2:3], v[2:3], v[46:47]

.LBB0_968:
	v_ashrrev_i32_e32 v15, 31, v14
	v_lshlrev_b64 v[6:7], 11, v[14:15]
	v_lshl_add_u64 v[44:45], v[12:13], 0, v[6:7]
	v_add_co_u32_e32 v46, vcc, 0x8000, v44
	s_nop 0
	v_addc_co_u32_e32 v47, vcc, 0, v45, vcc
	global_load_dwordx4 v[48:51], v[10:11], off
	global_load_dwordx4 v[64:67], v[44:45], off
	global_load_dwordx4 v[80:83], v[46:47], off
	global_load_dwordx4 v[52:55], v[10:11], off offset:64
	global_load_dwordx4 v[68:71], v[44:45], off offset:64
	global_load_dwordx4 v[84:87], v[46:47], off offset:64
	global_load_dwordx4 v[56:59], v[10:11], off offset:128
	global_load_dwordx4 v[72:75], v[44:45], off offset:128
	global_load_dwordx4 v[88:91], v[46:47], off offset:128
	global_load_dwordx4 v[60:63], v[10:11], off offset:192
	global_load_dwordx4 v[76:79], v[44:45], off offset:192
	global_load_dwordx4 v[92:95], v[46:47], off offset:192
	s_and_saveexec_b64 s[4:5], s[2:3]
	v_add_u32_e32 v104, v18, v14
	v_lshlrev_b32_e32 v104, 2, v104
	v_add_u32_e32 v105, 0x1000, v104
	v_add_u32_e32 v106, 0x2000, v104
	v_add_u32_e32 v107, 0x3000, v104
	global_load_dword v96, v104, s[38:39]
	global_load_dword v97, v104, s[38:39] offset:64
	global_load_dword v98, v105, s[38:39]
	global_load_dword v99, v105, s[38:39] offset:64
	global_load_dword v100, v106, s[38:39]
	global_load_dword v101, v106, s[38:39] offset:64
	global_load_dword v102, v107, s[38:39]
	global_load_dword v103, v107, s[38:39] offset:64
	s_or_b64 exec, exec, s[4:5]
	s_waitcnt vmcnt(0)
	v_mfma_f32_16x16x32_bf16 v[6:9], v[48:51], v[64:67], 0
	v_mfma_f32_16x16x32_bf16 v[2:5], v[48:51], v[80:83], 0
	v_mfma_f32_16x16x32_bf16 v[6:9], v[52:55], v[68:71], v[6:9]
	v_mfma_f32_16x16x32_bf16 v[2:5], v[52:55], v[84:87], v[2:5]
	v_mfma_f32_16x16x32_bf16 v[6:9], v[56:59], v[72:75], v[6:9]
	v_mfma_f32_16x16x32_bf16 v[2:5], v[56:59], v[88:91], v[2:5]
	v_mfma_f32_16x16x32_bf16 v[6:9], v[60:63], v[76:79], v[6:9]
	v_mfma_f32_16x16x32_bf16 v[2:5], v[60:63], v[92:95], v[2:5]
	s_nop 6
	ds_write_b128 v1, v[6:9]
	s_nop 0
	ds_write_b128 v1, v[2:5] offset:1024
	s_waitcnt lgkmcnt(0)
	s_barrier
	s_and_saveexec_b64 s[4:5], s[2:3]
	s_cbranch_execz .LBB0_970
	ds_read_b128 v[20:23], v16 offset:2048
	ds_read_b128 v[24:27], v16 offset:3072
	ds_read_b128 v[28:31], v16 offset:4096
	s_waitcnt lgkmcnt(2)
	v_pk_add_f32 v[32:33], v[6:7], v[20:21]
	s_waitcnt lgkmcnt(1)
	v_pk_add_f32 v[26:27], v[4:5], v[26:27]
	ds_read_b128 v[4:7], v16 offset:5120
	v_pk_add_f32 v[8:9], v[8:9], v[22:23]
	v_pk_add_f32 v[2:3], v[2:3], v[24:25]
	ds_read_b128 v[20:23], v16 offset:6144
	s_waitcnt lgkmcnt(2)
	v_pk_add_f32 v[24:25], v[8:9], v[30:31]
	s_waitcnt lgkmcnt(1)
	v_pk_add_f32 v[26:27], v[26:27], v[6:7]
	ds_read_b128 v[6:9], v16 offset:7168
	v_pk_add_f32 v[30:31], v[2:3], v[4:5]
	ds_read_b128 v[2:5], v16 offset:8192
	v_pk_add_f32 v[28:29], v[32:33], v[28:29]
	s_waitcnt lgkmcnt(2)
	v_pk_add_f32 v[24:25], v[24:25], v[22:23]
	v_pk_add_f32 v[28:29], v[28:29], v[20:21]
	s_waitcnt lgkmcnt(1)
	v_pk_add_f32 v[8:9], v[26:27], v[8:9]
	ds_read_b128 v[20:23], v16 offset:9216
	v_pk_add_f32 v[26:27], v[30:31], v[6:7]
	s_waitcnt lgkmcnt(1)
	v_pk_add_f32 v[30:31], v[24:25], v[4:5]
	ds_read_b128 v[4:7], v16 offset:10240
	v_pk_add_f32 v[2:3], v[28:29], v[2:3]
	s_waitcnt lgkmcnt(1)
	v_pk_add_f32 v[28:29], v[8:9], v[22:23]
	ds_read_b128 v[22:25], v16 offset:11264
	v_pk_add_f32 v[20:21], v[26:27], v[20:21]
	s_waitcnt lgkmcnt(1)
	v_pk_add_f32 v[26:27], v[30:31], v[6:7]
	ds_read_b128 v[6:9], v16 offset:12288
	v_pk_add_f32 v[30:31], v[2:3], v[4:5]
	ds_read_b128 v[2:5], v16 offset:13312
	s_waitcnt lgkmcnt(2)
	v_pk_add_f32 v[28:29], v[28:29], v[24:25]
	v_pk_add_f32 v[32:33], v[20:21], v[22:23]
	s_waitcnt lgkmcnt(1)
	v_pk_add_f32 v[8:9], v[26:27], v[8:9]
	ds_read_b128 v[20:23], v16 offset:14336
	ds_read_b128 v[24:27], v16 offset:15360
	v_pk_add_f32 v[6:7], v[30:31], v[6:7]
	s_waitcnt lgkmcnt(2)
	v_pk_add_f32 v[4:5], v[28:29], v[4:5]
	v_pk_add_f32 v[2:3], v[32:33], v[2:3]
	s_waitcnt lgkmcnt(1)
	v_pk_add_f32 v[8:9], v[8:9], v[22:23]
	v_pk_add_f32 v[6:7], v[6:7], v[20:21]
	s_waitcnt lgkmcnt(0)
	v_pk_add_f32 v[4:5], v[4:5], v[26:27]
	v_pk_add_f32 v[2:3], v[2:3], v[24:25]

.LBB0_1149:
	v_add_u32_e32 v2, s8, v1
	v_ashrrev_i32_e32 v3, 31, v2
	v_lshlrev_b64 v[6:7], 11, v[2:3]
	v_lshl_add_u64 v[46:47], v[12:13], 0, v[6:7]
	v_add_co_u32_e32 v48, vcc, 0x8000, v46
	s_nop 0
	v_addc_co_u32_e32 v49, vcc, 0, v47, vcc
	global_load_dwordx4 v[100:103], v[10:11], off
	global_load_dwordx4 v[104:107], v[46:47], off
	global_load_dwordx4 v[108:111], v[48:49], off
	global_load_dwordx4 v[112:115], v[10:11], off offset:64
	global_load_dwordx4 v[116:119], v[46:47], off offset:64
	global_load_dwordx4 v[120:123], v[48:49], off offset:64
	global_load_dwordx4 v[124:127], v[10:11], off offset:128
	global_load_dwordx4 v[128:131], v[46:47], off offset:128
	global_load_dwordx4 v[132:135], v[48:49], off offset:128
	global_load_dwordx4 v[136:139], v[10:11], off offset:192
	global_load_dwordx4 v[140:143], v[46:47], off offset:192
	global_load_dwordx4 v[144:147], v[48:49], off offset:192
	s_waitcnt vmcnt(0)
	v_mfma_f32_16x16x32_bf16 v[6:9], v[100:103], v[104:107], 0
	v_mfma_f32_16x16x32_bf16 v[2:5], v[100:103], v[108:111], 0
	v_mfma_f32_16x16x32_bf16 v[6:9], v[112:115], v[116:119], v[6:9]
	v_mfma_f32_16x16x32_bf16 v[2:5], v[112:115], v[120:123], v[2:5]
	v_mfma_f32_16x16x32_bf16 v[6:9], v[124:127], v[128:131], v[6:9]
	v_mfma_f32_16x16x32_bf16 v[2:5], v[124:127], v[132:135], v[2:5]
	v_mfma_f32_16x16x32_bf16 v[6:9], v[136:139], v[140:143], v[6:9]
	v_mfma_f32_16x16x32_bf16 v[2:5], v[136:139], v[144:147], v[2:5]
	s_nop 6
	ds_write_b128 v20, v[6:9]
	s_nop 0
	ds_write_b128 v20, v[2:5] offset:1024
	s_waitcnt lgkmcnt(0)
	s_barrier
	s_and_saveexec_b64 s[6:7], s[2:3]
	s_cbranch_execz .LBB0_1151
	ds_read_b128 v[22:25], v14 offset:2048
	ds_read_b128 v[26:29], v14 offset:3072
	ds_read_b128 v[30:33], v14 offset:4096
	s_waitcnt lgkmcnt(2)
	v_pk_add_f32 v[34:35], v[6:7], v[22:23]
	s_waitcnt lgkmcnt(1)
	v_pk_add_f32 v[28:29], v[4:5], v[28:29]
	ds_read_b128 v[4:7], v14 offset:5120
	v_pk_add_f32 v[8:9], v[8:9], v[24:25]
	v_pk_add_f32 v[2:3], v[2:3], v[26:27]
	ds_read_b128 v[22:25], v14 offset:6144
	s_waitcnt lgkmcnt(2)
	v_pk_add_f32 v[26:27], v[8:9], v[32:33]
	s_waitcnt lgkmcnt(1)
	v_pk_add_f32 v[28:29], v[28:29], v[6:7]
	ds_read_b128 v[6:9], v14 offset:7168
	v_pk_add_f32 v[32:33], v[2:3], v[4:5]
	ds_read_b128 v[2:5], v14 offset:8192
	v_pk_add_f32 v[30:31], v[34:35], v[30:31]
	s_waitcnt lgkmcnt(2)
	v_pk_add_f32 v[26:27], v[26:27], v[24:25]
	v_pk_add_f32 v[30:31], v[30:31], v[22:23]
	s_waitcnt lgkmcnt(1)
	v_pk_add_f32 v[8:9], v[28:29], v[8:9]
	ds_read_b128 v[22:25], v14 offset:9216
	v_pk_add_f32 v[28:29], v[32:33], v[6:7]
	s_waitcnt lgkmcnt(1)
	v_pk_add_f32 v[32:33], v[26:27], v[4:5]
	ds_read_b128 v[4:7], v14 offset:10240
	v_pk_add_f32 v[2:3], v[30:31], v[2:3]
	s_waitcnt lgkmcnt(1)
	v_pk_add_f32 v[30:31], v[8:9], v[24:25]
	ds_read_b128 v[24:27], v14 offset:11264
	v_pk_add_f32 v[22:23], v[28:29], v[22:23]
	s_waitcnt lgkmcnt(1)
	v_pk_add_f32 v[28:29], v[32:33], v[6:7]
	ds_read_b128 v[6:9], v14 offset:12288
	v_pk_add_f32 v[32:33], v[2:3], v[4:5]
	ds_read_b128 v[2:5], v14 offset:13312
	s_waitcnt lgkmcnt(2)
	v_pk_add_f32 v[30:31], v[30:31], v[26:27]
	v_pk_add_f32 v[34:35], v[22:23], v[24:25]
	s_waitcnt lgkmcnt(1)
	v_pk_add_f32 v[8:9], v[28:29], v[8:9]
	ds_read_b128 v[22:25], v14 offset:14336
	ds_read_b128 v[26:29], v14 offset:15360
	v_pk_add_f32 v[6:7], v[32:33], v[6:7]
	s_waitcnt lgkmcnt(2)
	v_pk_add_f32 v[4:5], v[30:31], v[4:5]
	v_pk_add_f32 v[2:3], v[34:35], v[2:3]
	s_waitcnt lgkmcnt(1)
	v_pk_add_f32 v[8:9], v[8:9], v[24:25]
	v_pk_add_f32 v[6:7], v[6:7], v[22:23]
	s_waitcnt lgkmcnt(0)
	v_pk_add_f32 v[4:5], v[4:5], v[28:29]
	v_pk_add_f32 v[2:3], v[2:3], v[26:27]
